# layer-1 weight conversion moved out of phase 0: done by the workgroups that have no unit in the tail rounds of phases 1, 5 and 11 (same conversion code, different work distribution)
# speedup vs baseline: 1.0281x; 1.0258x over previous
; #define LAS __attribute__((address_space(3)))
; DI CP* kparams() { CP* kp = (CP*)__builtin_amdgcn_kernarg_segment_ptr(); asm volatile("" : "+s"(kp)); return kp; }
; DI int lane_id() { int l = __builtin_amdgcn_mbcnt_hi(-1, __builtin_amdgcn_mbcnt_lo(-1, 0)); asm volatile("" : "+v"(l)); return l; }
; DI unsigned xb_add(unsigned* q, unsigned v) { return __hip_atomic_fetch_add(q, v, __ATOMIC_RELAXED, __HIP_MEMORY_SCOPE_AGENT); }
; DI unsigned xb_xcc_id() { return (unsigned)__builtin_amdgcn_s_getreg((3 << 11) | 20) & 0xFu; }
; __global__ void __launch_bounds__(NTHR, 2) mega(Params pv) {
;     extern __shared__ __attribute__((aligned(16))) unsigned char lds_raw[];
;     LAS unsigned char* lds = (LAS unsigned char*)lds_raw;
;     cg::grid_group grid = cg::this_grid();
;     const int wid = __builtin_amdgcn_readfirstlane((int)threadIdx.x >> 6);
;     const int ph_lo = pv.ph_lo, ph_hi = pv.ph_hi;
;     if (ph_lo == 0x7fffffff) grid.sync();
;     if (ph_hi - ph_lo > 1) {
;         if (wid == 0 && lane_id() == 0) { volatile LAS unsigned* st = (volatile LAS unsigned*)(lds + LDS_MAIN); st[0] = 0u; st[1] = 0u;
;             CP& p0 = *kparams(); (void)xb_add(&((unsigned*)(p0.ws + OFF_BAR))[XB_XCNT(xb_xcc_id())], 1u); }
_Z4mega6Params:
	s_mov_b32 s98, 0
	s_load_dwordx2 s[34:35], s[0:1], 0xb0
	s_load_dword s7, s[0:1], 0xb8
	s_add_u32 s4, s0, 0xb8
	s_addc_u32 s5, s1, 0
	v_and_b32_e32 v1, 0x3ff, v0
	s_mov_b32 s6, s2
	s_movk_i32 s2, 0x3ff
	s_waitcnt lgkmcnt(0)
	s_cmp_lg_u32 s34, 0x7fffffff
	v_readfirstlane_b32 s88, v1
	s_cbranch_scc1 .LBB0_12
	v_lshrrev_b32_e32 v2, 20, v0
	v_lshrrev_b32_e32 v0, 10, v0
	v_or_b32_e32 v0, v0, v2
	v_and_or_b32 v0, v0, s2, v1
	v_cmp_eq_u32_e32 vcc, 0, v0
	s_barrier
	s_and_saveexec_b64 s[2:3], vcc
	s_cbranch_execz .LBB0_11
	buffer_wbl2 sc1
	s_load_dwordx2 s[4:5], s[4:5], 0x58
	s_mov_b64 s[8:9], exec
	v_mbcnt_lo_u32_b32 v0, s8, 0
	v_mbcnt_hi_u32_b32 v0, s9, v0
	v_cmp_eq_u32_e32 vcc, 0, v0
	s_waitcnt lgkmcnt(0)
	s_load_dword s12, s[4:5], 0x28
	s_and_saveexec_b64 s[10:11], vcc
	s_cbranch_execz .LBB0_4
	s_bcnt1_i32_b64 s8, s[8:9]
	v_mov_b32_e32 v1, 0
	v_mov_b32_e32 v2, s8
	global_atomic_add v1, v1, v2, s[4:5] offset:32 sc0

; #define LAS __attribute__((address_space(3)))
; DI int lane_id() { int l = __builtin_amdgcn_mbcnt_hi(-1, __builtin_amdgcn_mbcnt_lo(-1, 0)); asm volatile("" : "+v"(l)); return l; }
; DI void phase0(CP& p, LAS unsigned char* lds, int wid) {
;     const int lane = lane_id(), tid = wid * 64 + lane;
;     constexpr int NCONV = 5520, NXROW = 8192;
;     const int gw = blockIdx.x * 8 + wid, nw = gridDim.x * 8;
;     for (int it0 = gw; it0 < NCONV + NXROW; it0 += nw) {
;         const int it = it0 < NCONV ? NCONV - 1 - it0 : it0;
;         if (it < NCONV) {
.Lconv_entry:
	s_lshl_b32 s2, s6, 3
	v_mbcnt_hi_u32_b32 v5, -1, v254
	s_add_i32 s89, s33, s2
	s_cmp_lg_u32 s98, 0
	s_cbranch_scc1 .Lconv_ext
	s_addk_i32 s89, 0xac0
	s_movk_i32 s101, 0x358f
	s_branch .Lconv_go
.Lconv_ext:
	s_mov_b32 s89, s99
.Lconv_go:
	s_mov_b64 s[38:39], s[0:1]
	s_mov_b32 s41, 0
	v_mov_b32_e32 v0, v5
	s_cmp_gt_i32 s89, s101
	s_cbranch_scc1 .LBB0_225
	s_load_dwordx4 s[24:27], s[38:39], 0x0
	s_load_dwordx2 s[4:5], s[38:39], 0x10
	s_load_dwordx2 s[44:45], s[38:39], 0xa8
	s_load_dwordx4 s[28:31], s[38:39], 0x90
	s_lshl_b32 s90, s7, 3
	s_cmp_eq_u32 s98, 0
	s_cselect_b32 s90, s90, s100
	v_ashrrev_i32_e32 v1, 31, v0
	s_waitcnt lgkmcnt(0)
	v_mov_b32_e32 v2, s24
	s_add_u32 s91, s44, 0xcd00000
	s_addc_u32 s92, s45, 0
	s_add_u32 s8, s28, 0x2c00000
	v_writelane_b32 v255, s8, 0
	s_addc_u32 s8, s29, 0
	v_writelane_b32 v255, s8, 1
	s_add_u32 s4, s4, 0x2000
	v_writelane_b32 v255, s4, 2
	s_addc_u32 s4, s5, 0
	s_add_u32 s24, s44, 0x6300000
	v_mov_b32_e32 v3, s25
	s_addc_u32 s25, s45, 0
	s_add_u32 s46, s44, 0x6100000
	s_addc_u32 s47, s45, 0
	s_add_u32 s48, s44, 0x5f00000
	s_addc_u32 s49, s45, 0
	v_lshl_add_u64 v[2:3], v[0:1], 4, v[2:3]
	v_and_b32_e32 v1, 64, v5
	s_add_u32 s50, s44, 0x5c00000
	v_lshlrev_b32_e32 v4, 1, v0
	v_and_b32_e32 v9, 3, v0
	v_add_u32_e32 v8, 64, v1
	s_addc_u32 s51, s45, 0
	v_and_or_b32 v4, v4, 24, v9
	v_xor_b32_e32 v9, 1, v5
	s_add_u32 s52, s26, 0x2000
	v_cmp_lt_i32_e32 vcc, v9, v8
	s_addc_u32 s53, s27, 0
	s_add_u32 s54, s44, 0x5700000
	v_cndmask_b32_e32 v9, v5, v9, vcc
	v_lshlrev_b32_e32 v224, 2, v9
	v_xor_b32_e32 v9, 2, v5
	s_addc_u32 s55, s45, 0
	v_cmp_lt_i32_e32 vcc, v9, v8
	s_add_u32 s58, s44, 0x5600000
	s_addc_u32 s59, s45, 0
	v_cndmask_b32_e32 v9, v5, v9, vcc
	v_lshlrev_b32_e32 v225, 2, v9
	v_xor_b32_e32 v9, 4, v5
	s_add_u32 s60, s44, 0x4000000
	v_cmp_lt_i32_e32 vcc, v9, v8
	s_addc_u32 s61, s45, 0
	s_add_u32 s62, s44, 0x1400000
	v_cndmask_b32_e32 v9, v5, v9, vcc
	v_lshlrev_b32_e32 v226, 2, v9
	v_xor_b32_e32 v9, 8, v5
	s_addc_u32 s63, s45, 0
	v_cmp_lt_i32_e32 vcc, v9, v8
	s_add_u32 s64, s44, 0xc00000
	v_ashrrev_i32_e32 v220, 3, v0
	v_cndmask_b32_e32 v9, v5, v9, vcc
	s_addc_u32 s65, s45, 0
	v_and_b32_e32 v7, -4, v220
	v_lshlrev_b32_e32 v227, 2, v9
	v_xor_b32_e32 v9, 16, v5
	v_writelane_b32 v255, s4, 3
	s_add_u32 s66, s44, 0x800000
	s_mul_i32 s4, s33, 0x2400
	v_add_u32_e32 v221, v4, v7
	v_and_b32_e32 v4, 16, v0
	v_cmp_lt_i32_e32 vcc, v9, v8
	s_addc_u32 s67, s45, 0
	s_add_i32 s40, s4, 0
	v_lshlrev_b32_e32 v6, 2, v0
	s_movk_i32 s8, 0xff80
	v_cmp_eq_u32_e64 s[4:5], 0, v4
	v_bfe_u32 v4, v0, 3, 5
	v_ashrrev_i32_e32 v7, 1, v0
	v_cndmask_b32_e32 v9, v5, v9, vcc
	v_and_or_b32 v223, v7, s8, v4
	s_movk_i32 s8, 0x90
	v_ashrrev_i32_e32 v7, 31, v6
	v_lshlrev_b32_e32 v228, 2, v9
	v_xor_b32_e32 v9, 32, v5
	v_and_b32_e32 v1, 0xffffff80, v6
	v_mul_lo_u32 v10, v0, s8
	v_cmp_lt_i32_e32 vcc, v9, v8
	v_mul_lo_u32 v8, v220, s8
	v_lshl_add_u64 v[6:7], v[6:7], 1, s[44:45]
	s_mov_b64 s[8:9], 0xad00000
	s_load_dwordx2 s[56:57], s[38:39], 0x20
	v_lshl_add_u64 v[6:7], v[6:7], 0, s[8:9]
	s_load_dwordx16 s[8:23], s[38:39], 0x50
	v_lshlrev_b32_e32 v4, 4, v0
	v_and_b32_e32 v4, 0x70, v4
	v_add_u32_e32 v11, s40, v4
	v_cndmask_b32_e32 v5, v5, v9, vcc
	v_mov_b32_e32 v9, 0
	v_cmp_eq_u32_e64 s[2:3], 0, v0
	v_and_or_b32 v1, v0, 31, v1
	v_lshlrev_b32_e32 v229, 2, v5
	v_mov_b32_e32 v5, v9
	s_movk_i32 s97, 0x400
	v_add_u32_e32 v230, s40, v10
	v_add_u32_e32 v231, v11, v8
	s_mov_b64 s[68:69], 0x80
	s_branch .LBB0_23
.LBB0_22:
	s_add_i32 s89, s89, s90
	s_cmp_gt_i32 s89, s101
	s_cbranch_scc1 .LBB0_225

; DI void phase0(CP& p, LAS unsigned char* lds, int wid) {
;     ...
;     const int gt = blockIdx.x * NTHR + tid, gs = gridDim.x * NTHR;
;     for (int i = gt; i < 7 * 8192; i += gs) SSQ(1)[i] = 0.f;
.LBB0_225:
	s_cmp_eq_u32 s98, 1
	s_cbranch_scc1 .Lconv_ret_1
	s_cmp_eq_u32 s98, 2
	s_cbranch_scc1 .Lconv_ret_2
	s_cmp_eq_u32 s98, 3
	s_cbranch_scc1 .Lconv_tramp_out
	s_load_dwordx2 s[4:5], s[38:39], 0xa8
	s_and_b32 s2, s88, 0xffffffc0
	s_lshl_b32 s3, s6, 9
	s_add_i32 s2, s2, s3
	v_add_u32_e32 v2, s2, v0
	s_mov_b32 s2, 0xe000
	s_waitcnt lgkmcnt(0)
	s_lshl_b32 s10, s7, 9
	v_cmp_gt_i32_e32 vcc, s2, v2
	s_and_saveexec_b64 s[8:9], vcc
	s_cbranch_execz .LBB0_233
	v_cvt_f32_u32_e32 v1, s10
	v_add_u32_e32 v3, s10, v2
	v_mov_b32_e32 v4, s10
	v_cmp_gt_i32_e32 vcc, s2, v3
	v_rcp_iflag_f32_e32 v1, v1
	s_sub_i32 s11, 0, s10
	v_max_i32_e32 v5, 0xe000, v3
	v_addc_co_u32_e64 v4, s[2:3], v2, v4, vcc
	v_mul_f32_e32 v1, 0x4f7ffffe, v1
	v_cvt_u32_f32_e32 v1, v1
	v_sub_u32_e32 v4, v5, v4
	s_mov_b64 s[12:13], -1
	v_mul_lo_u32 v5, s11, v1
	v_mul_hi_u32 v5, v1, v5
	v_add_u32_e32 v1, v1, v5
	v_mul_hi_u32 v1, v4, v1
	v_mul_lo_u32 v5, v1, s10
	v_sub_u32_e32 v4, v4, v5
	v_add_u32_e32 v6, 1, v1
	v_cmp_le_u32_e64 s[2:3], s10, v4
	v_subrev_u32_e32 v5, s10, v4
	s_nop 0
	v_cndmask_b32_e64 v1, v1, v6, s[2:3]
	v_cndmask_b32_e64 v4, v4, v5, s[2:3]
	v_add_u32_e32 v5, 1, v1
	v_cmp_le_u32_e64 s[2:3], s10, v4
	v_mov_b32_e32 v4, v2
	s_nop 0
	v_cndmask_b32_e64 v1, v1, v5, s[2:3]
	v_addc_co_u32_e32 v1, vcc, 1, v1, vcc
	v_cmp_lt_u32_e32 vcc, 1, v1
	s_and_saveexec_b64 s[2:3], vcc
	s_cbranch_execz .LBB0_230
	s_add_u32 s12, s4, 0xcd08000
	s_addc_u32 s13, s5, 0
	v_and_b32_e32 v6, -2, v1
	s_lshl_b32 s11, s7, 10
	s_mov_b32 s16, s11
	s_mov_b64 s[14:15], 0
	v_mov_b32_e32 v7, 0
	v_mov_b32_e32 v8, v6
	v_mov_b64_e32 v[4:5], v[2:3]

; #define LAS __attribute__((address_space(3)))
; DI int lane_id() { int l = __builtin_amdgcn_mbcnt_hi(-1, __builtin_amdgcn_mbcnt_lo(-1, 0)); asm volatile("" : "+v"(l)); return l; }
; DI unsigned xb_add(unsigned* q, unsigned v) { return __hip_atomic_fetch_add(q, v, __ATOMIC_RELAXED, __HIP_MEMORY_SCOPE_AGENT); }
; DI unsigned xb_xcc_id() { return (unsigned)__builtin_amdgcn_s_getreg((3 << 11) | 20) & 0xFu; }
; DI void grid_bar(unsigned* bar, volatile LAS unsigned* st, int wid) {
;     asm volatile("s_waitcnt vmcnt(0)" ::: "memory");
;     __syncthreads();
;     if (wid == 0) {
;         if (lane_id() == 0) {
;             __builtin_amdgcn_s_waitcnt(0);
;             const unsigned x = xb_xcc_id();
;             unsigned nloc = st[0], nx = st[1];
;             if (nloc == 0u) { xcd_barrier_complete(bar, x, nloc, nx); st[0] = nloc; st[1] = nx; }
;             const unsigned old = xb_add(&bar[XB_XSUB(x)], 1u);
;             const unsigned gen = old / nloc;
;             if (old + 1u == (gen + 1u) * nloc) {
.LBB0_397:
	s_barrier
	s_cmpk_eq_i32 s7, 0x100
	s_cbranch_scc0 .Lconv_skip_1
	s_and_b32 s2, s6, 31
	s_cmp_lt_u32 s2, 16
	s_cbranch_scc1 .Lconv_skip_1
	s_lshr_b32 s3, s6, 5
	s_lshl_b32 s3, s3, 4
	s_add_i32 s2, s2, s3
	s_add_i32 s2, s2, -16
	s_lshl_b32 s2, s2, 3
	s_add_i32 s99, s2, s33
	s_addk_i32 s99, 1728
	s_movk_i32 s101, 2751
	s_movk_i32 s100, 0x4000
	s_mov_b32 s98, 1
	s_branch .Lconv_entry
.Lconv_ret_1:
	s_mov_b32 s98, 0
	s_cmp_lt_i32 s34, 2
	s_cselect_b64 s[8:9], -1, 0
	s_cmp_gt_i32 s35, 1
	s_cselect_b64 s[2:3], -1, 0
	s_and_b64 s[8:9], s[8:9], s[2:3]
.Lconv_skip_1:
.LBB0_398:
	s_cmp_gt_i32 s35, 2
	s_cselect_b64 s[2:3], -1, 0
	s_and_b64 s[4:5], s[8:9], s[2:3]
	s_andn2_b64 vcc, exec, s[4:5]
	s_cbranch_vccnz .LBB0_454
	s_mov_b64 s[8:9], s[0:1]
	s_waitcnt vmcnt(0)
	s_cmp_gt_u32 s88, 63
	s_waitcnt vmcnt(0) lgkmcnt(0)
	s_barrier
	s_cbranch_scc1 .LBB0_453
	v_mbcnt_hi_u32_b32 v0, -1, v254
	s_nop 0
	v_cmp_eq_u32_e32 vcc, 0, v0
	s_and_saveexec_b64 s[4:5], vcc
	s_cbranch_execz .LBB0_452
	s_add_i32 s11, 0, 0x20000
	v_mov_b32_e32 v0, s11
	s_load_dwordx2 s[8:9], s[8:9], 0xa8
	s_waitcnt vmcnt(0) expcnt(0) lgkmcnt(0)
	s_getreg_b32 s10, hwreg(HW_REG_XCC_ID, 0, 4)
	ds_read_b32 v2, v0
	s_add_i32 s11, 0, 0x20004
	v_mov_b32_e32 v0, s11
	ds_read_b32 v0, v0
	s_and_b32 s54, s10, 15
	s_waitcnt lgkmcnt(1)
	v_cmp_ne_u32_e32 vcc, 0, v2
	s_cbranch_vccnz .LBB0_416
	s_add_u32 s10, s8, 0xcd80200
	s_addc_u32 s11, s9, 0
	s_add_u32 s12, s8, 0xcd80400
	s_addc_u32 s13, s9, 0
	s_add_u32 s14, s8, 0xcd80500
	s_addc_u32 s15, s9, 0
	s_add_u32 s16, s8, 0xcd80600
	s_addc_u32 s17, s9, 0
	s_add_u32 s18, s8, 0xcd80700
	s_addc_u32 s19, s9, 0
	s_add_u32 s20, s8, 0xcd80800
	s_addc_u32 s21, s9, 0
	s_add_u32 s22, s8, 0xcd80900
	s_addc_u32 s23, s9, 0
	s_add_u32 s24, s8, 0xcd80a00
	s_addc_u32 s25, s9, 0
	s_add_u32 s26, s8, 0xcd80b00
	s_addc_u32 s27, s9, 0
	s_add_u32 s28, s8, 0xcd80c00
	s_addc_u32 s29, s9, 0
	s_add_u32 s30, s8, 0xcd80d00
	s_addc_u32 s31, s9, 0
	s_add_u32 s36, s8, 0xcd80e00
	s_addc_u32 s37, s9, 0
	s_add_u32 s38, s8, 0xcd80f00
	s_addc_u32 s39, s9, 0
	s_add_u32 s40, s8, 0xcd81000
	s_addc_u32 s41, s9, 0
	s_add_u32 s42, s8, 0xcd81100
	s_addc_u32 s43, s9, 0
	s_add_u32 s44, s8, 0xcd81200
	s_addc_u32 s45, s9, 0
	s_add_u32 s46, s8, 0xcd81300
	s_addc_u32 s47, s9, 0
	s_mov_b32 s55, 1
	v_mov_b32_e32 v16, 0
	s_branch .LBB0_404

; #define LAS __attribute__((address_space(3)))
; DI int lane_id() { int l = __builtin_amdgcn_mbcnt_hi(-1, __builtin_amdgcn_mbcnt_lo(-1, 0)); asm volatile("" : "+v"(l)); return l; }
; DI unsigned xb_add(unsigned* q, unsigned v) { return __hip_atomic_fetch_add(q, v, __ATOMIC_RELAXED, __HIP_MEMORY_SCOPE_AGENT); }
; DI unsigned xb_xcc_id() { return (unsigned)__builtin_amdgcn_s_getreg((3 << 11) | 20) & 0xFu; }
; DI void grid_bar(unsigned* bar, volatile LAS unsigned* st, int wid) {
;     asm volatile("s_waitcnt vmcnt(0)" ::: "memory");
;     __syncthreads();
;     if (wid == 0) {
;         if (lane_id() == 0) {
;             __builtin_amdgcn_s_waitcnt(0);
;             const unsigned x = xb_xcc_id();
;             unsigned nloc = st[0], nx = st[1];
;             if (nloc == 0u) { xcd_barrier_complete(bar, x, nloc, nx); st[0] = nloc; st[1] = nx; }
;             const unsigned old = xb_add(&bar[XB_XSUB(x)], 1u);
;             const unsigned gen = old / nloc;
;             if (old + 1u == (gen + 1u) * nloc) {
.LBB0_709:
	s_barrier
	s_cmpk_eq_i32 s7, 0x100
	s_cbranch_scc0 .Lconv_skip_2
	s_and_b32 s2, s6, 31
	s_cmp_lt_u32 s2, 16
	s_cbranch_scc1 .Lconv_skip_2
	s_lshr_b32 s3, s6, 5
	s_lshl_b32 s3, s3, 4
	s_add_i32 s2, s2, s3
	s_add_i32 s2, s2, -16
	s_lshl_b32 s2, s2, 3
	s_add_i32 s99, s2, s33
	s_addk_i32 s99, 704
	s_movk_i32 s101, 1727
	s_movk_i32 s100, 0x4000
	s_mov_b32 s98, 2
	s_branch .Lconv_entry
.Lconv_ret_2:
	s_mov_b32 s98, 0
	s_cmp_lt_i32 s34, 6
	s_cselect_b64 s[4:5], -1, 0
	s_cmp_gt_i32 s35, 5
	s_cselect_b64 s[2:3], -1, 0
	s_and_b64 s[4:5], s[4:5], s[2:3]
	s_branch .Lconv_tramp_skip
.Lconv_tramp_in:
	s_branch .Lconv_entry
.Lconv_tramp_out:
	s_branch .Lconv_ret_3
.Lconv_tramp_skip:
.Lconv_skip_2:
.LBB0_710:
	s_cmp_gt_i32 s35, 6
	s_cselect_b64 s[2:3], -1, 0
	s_and_b64 s[4:5], s[4:5], s[2:3]
	s_andn2_b64 vcc, exec, s[4:5]
	s_cbranch_vccnz .LBB0_766
	s_mov_b64 s[8:9], s[0:1]
	s_waitcnt vmcnt(0)
	s_cmp_gt_u32 s88, 63
	s_waitcnt vmcnt(0) lgkmcnt(0)
	s_barrier
	s_cbranch_scc1 .LBB0_765
	v_mbcnt_hi_u32_b32 v0, -1, v254
	s_nop 0
	v_cmp_eq_u32_e32 vcc, 0, v0
	s_and_saveexec_b64 s[4:5], vcc
	s_cbranch_execz .LBB0_764
	s_add_i32 s11, 0, 0x20000
	v_mov_b32_e32 v0, s11
	s_load_dwordx2 s[8:9], s[8:9], 0xa8
	s_waitcnt vmcnt(0) expcnt(0) lgkmcnt(0)
	s_getreg_b32 s10, hwreg(HW_REG_XCC_ID, 0, 4)
	ds_read_b32 v2, v0
	s_add_i32 s11, 0, 0x20004
	v_mov_b32_e32 v0, s11
	ds_read_b32 v0, v0
	s_and_b32 s54, s10, 15
	s_waitcnt lgkmcnt(1)
	v_cmp_ne_u32_e32 vcc, 0, v2
	s_cbranch_vccnz .LBB0_728
	s_add_u32 s10, s8, 0xcd80200
	s_addc_u32 s11, s9, 0
	s_add_u32 s12, s8, 0xcd80400
	s_addc_u32 s13, s9, 0
	s_add_u32 s14, s8, 0xcd80500
	s_addc_u32 s15, s9, 0
	s_add_u32 s16, s8, 0xcd80600
	s_addc_u32 s17, s9, 0
	s_add_u32 s18, s8, 0xcd80700
	s_addc_u32 s19, s9, 0
	s_add_u32 s20, s8, 0xcd80800
	s_addc_u32 s21, s9, 0
	s_add_u32 s22, s8, 0xcd80900
	s_addc_u32 s23, s9, 0
	s_add_u32 s24, s8, 0xcd80a00
	s_addc_u32 s25, s9, 0
	s_add_u32 s26, s8, 0xcd80b00
	s_addc_u32 s27, s9, 0
	s_add_u32 s28, s8, 0xcd80c00
	s_addc_u32 s29, s9, 0
	s_add_u32 s30, s8, 0xcd80d00
	s_addc_u32 s31, s9, 0
	s_add_u32 s36, s8, 0xcd80e00
	s_addc_u32 s37, s9, 0
	s_add_u32 s38, s8, 0xcd80f00
	s_addc_u32 s39, s9, 0
	s_add_u32 s40, s8, 0xcd81000
	s_addc_u32 s41, s9, 0
	s_add_u32 s42, s8, 0xcd81100
	s_addc_u32 s43, s9, 0
	s_add_u32 s44, s8, 0xcd81200
	s_addc_u32 s45, s9, 0
	s_add_u32 s46, s8, 0xcd81300
	s_addc_u32 s47, s9, 0
	s_mov_b32 s55, 1
	v_mov_b32_e32 v16, 0
	s_branch .LBB0_716

; #define LAS __attribute__((address_space(3)))
; DI int lane_id() { int l = __builtin_amdgcn_mbcnt_hi(-1, __builtin_amdgcn_mbcnt_lo(-1, 0)); asm volatile("" : "+v"(l)); return l; }
; DI unsigned xb_add(unsigned* q, unsigned v) { return __hip_atomic_fetch_add(q, v, __ATOMIC_RELAXED, __HIP_MEMORY_SCOPE_AGENT); }
; DI unsigned xb_xcc_id() { return (unsigned)__builtin_amdgcn_s_getreg((3 << 11) | 20) & 0xFu; }
; DI void grid_bar(unsigned* bar, volatile LAS unsigned* st, int wid) {
;     asm volatile("s_waitcnt vmcnt(0)" ::: "memory");
;     __syncthreads();
;     if (wid == 0) {
;         if (lane_id() == 0) {
;             __builtin_amdgcn_s_waitcnt(0);
;             const unsigned x = xb_xcc_id();
;             unsigned nloc = st[0], nx = st[1];
;             if (nloc == 0u) { xcd_barrier_complete(bar, x, nloc, nx); st[0] = nloc; st[1] = nx; }
;             const unsigned old = xb_add(&bar[XB_XSUB(x)], 1u);
;             const unsigned gen = old / nloc;
;             if (old + 1u == (gen + 1u) * nloc) {
.LBB0_1264:
	s_barrier
	s_cmpk_eq_i32 s7, 0x100
	s_cbranch_scc0 .Lconv_skip_3
	s_and_b32 s2, s6, 31
	s_cmp_lt_u32 s2, 16
	s_cbranch_scc1 .Lconv_skip_3
	s_lshr_b32 s3, s6, 5
	s_lshl_b32 s3, s3, 4
	s_add_i32 s2, s2, s3
	s_add_i32 s2, s2, -16
	s_lshl_b32 s2, s2, 3
	s_add_i32 s99, s2, s33
	s_addk_i32 s99, 0
	s_movk_i32 s101, 703
	s_movk_i32 s100, 0x4000
	s_mov_b32 s98, 3
	s_branch .Lconv_tramp_in
.Lconv_ret_3:
	s_mov_b32 s98, 0
	s_cmp_lt_i32 s34, 12
	s_cselect_b64 s[4:5], -1, 0
	s_cmp_gt_i32 s35, 11
	s_cselect_b64 s[2:3], -1, 0
	s_and_b64 s[4:5], s[4:5], s[2:3]
.Lconv_skip_3:
.LBB0_1265:
	s_cmp_gt_i32 s35, 12
	s_cselect_b64 s[2:3], -1, 0
	s_and_b64 s[4:5], s[4:5], s[2:3]
	s_andn2_b64 vcc, exec, s[4:5]
	s_cbranch_vccnz .LBB0_1321
	s_mov_b64 s[8:9], s[0:1]
	s_waitcnt vmcnt(0)
	s_cmp_gt_u32 s88, 63
	s_waitcnt vmcnt(0) lgkmcnt(0)
	s_barrier
	s_cbranch_scc1 .LBB0_1320
	v_mbcnt_hi_u32_b32 v0, -1, v254
	s_nop 0
	v_cmp_eq_u32_e32 vcc, 0, v0
	s_and_saveexec_b64 s[4:5], vcc
	s_cbranch_execz .LBB0_1319
	s_add_i32 s11, 0, 0x20000
	v_mov_b32_e32 v0, s11
	s_load_dwordx2 s[8:9], s[8:9], 0xa8
	s_waitcnt vmcnt(0) expcnt(0) lgkmcnt(0)
	s_getreg_b32 s10, hwreg(HW_REG_XCC_ID, 0, 4)
	ds_read_b32 v2, v0
	s_add_i32 s11, 0, 0x20004
	v_mov_b32_e32 v0, s11
	ds_read_b32 v0, v0
	s_and_b32 s54, s10, 15
	s_waitcnt lgkmcnt(1)
	v_cmp_ne_u32_e32 vcc, 0, v2
	s_cbranch_vccnz .LBB0_1283
	s_add_u32 s10, s8, 0xcd80200
	s_addc_u32 s11, s9, 0
	s_add_u32 s12, s8, 0xcd80400
	s_addc_u32 s13, s9, 0
	s_add_u32 s14, s8, 0xcd80500
	s_addc_u32 s15, s9, 0
	s_add_u32 s16, s8, 0xcd80600
	s_addc_u32 s17, s9, 0
	s_add_u32 s18, s8, 0xcd80700
	s_addc_u32 s19, s9, 0
	s_add_u32 s20, s8, 0xcd80800
	s_addc_u32 s21, s9, 0
	s_add_u32 s22, s8, 0xcd80900
	s_addc_u32 s23, s9, 0
	s_add_u32 s24, s8, 0xcd80a00
	s_addc_u32 s25, s9, 0
	s_add_u32 s26, s8, 0xcd80b00
	s_addc_u32 s27, s9, 0
	s_add_u32 s28, s8, 0xcd80c00
	s_addc_u32 s29, s9, 0
	s_add_u32 s30, s8, 0xcd80d00
	s_addc_u32 s31, s9, 0
	s_add_u32 s36, s8, 0xcd80e00
	s_addc_u32 s37, s9, 0
	s_add_u32 s38, s8, 0xcd80f00
	s_addc_u32 s39, s9, 0
	s_add_u32 s40, s8, 0xcd81000
	s_addc_u32 s41, s9, 0
	s_add_u32 s42, s8, 0xcd81100
	s_addc_u32 s43, s9, 0
	s_add_u32 s44, s8, 0xcd81200
	s_addc_u32 s45, s9, 0
	s_add_u32 s46, s8, 0xcd81300
	s_addc_u32 s47, s9, 0
	s_mov_b32 s55, 1
	v_mov_b32_e32 v16, 0
	s_branch .LBB0_1271

; __global__ void __launch_bounds__(NTHR, 2) mega(Params pv) {
	.amdhsa_kernel _Z4mega6Params
		.amdhsa_group_segment_fixed_size 0
		.amdhsa_private_segment_fixed_size 0
		.amdhsa_kernarg_size 440
		.amdhsa_user_sgpr_count 2
		.amdhsa_user_sgpr_dispatch_ptr 0
		.amdhsa_user_sgpr_queue_ptr 0
		.amdhsa_user_sgpr_kernarg_segment_ptr 1
		.amdhsa_user_sgpr_dispatch_id 0
		.amdhsa_user_sgpr_kernarg_preload_length 0
		.amdhsa_user_sgpr_kernarg_preload_offset 0
		.amdhsa_user_sgpr_private_segment_size 0
		.amdhsa_uses_dynamic_stack 0
		.amdhsa_enable_private_segment 0
		.amdhsa_system_sgpr_workgroup_id_x 1
		.amdhsa_system_sgpr_workgroup_id_y 0
		.amdhsa_system_sgpr_workgroup_id_z 0
		.amdhsa_system_sgpr_workgroup_info 0
		.amdhsa_system_vgpr_workitem_id 2
		.amdhsa_next_free_vgpr 256
		.amdhsa_next_free_sgpr 102
		.amdhsa_accum_offset 256
		.amdhsa_reserve_vcc 1
		.amdhsa_float_round_mode_32 0
		.amdhsa_float_round_mode_16_64 0
		.amdhsa_float_denorm_mode_32 3
		.amdhsa_float_denorm_mode_16_64 3
		.amdhsa_dx10_clamp 1
		.amdhsa_ieee_mode 1
		.amdhsa_fp16_overflow 0
		.amdhsa_tg_split 0
		.amdhsa_exception_fp_ieee_invalid_op 0
		.amdhsa_exception_fp_denorm_src 0
		.amdhsa_exception_fp_ieee_div_zero 0
		.amdhsa_exception_fp_ieee_overflow 0
		.amdhsa_exception_fp_ieee_underflow 0
		.amdhsa_exception_fp_ieee_inexact 0
		.amdhsa_exception_int_div_zero 0
	.end_amdhsa_kernel

; __global__ void __launch_bounds__(NTHR, 2) mega(Params pv) {
.Lfunc_end0:
	.size	_Z4mega6Params, .Lfunc_end0-_Z4mega6Params
	.set _Z4mega6Params.num_vgpr, 256
	.set _Z4mega6Params.num_agpr, 0
	.set _Z4mega6Params.numbered_sgpr, 102
	.set _Z4mega6Params.num_named_barrier, 0
	.set _Z4mega6Params.private_seg_size, 0
	.set _Z4mega6Params.uses_vcc, 1
	.set _Z4mega6Params.uses_flat_scratch, 0
	.set _Z4mega6Params.has_dyn_sized_stack, 0
	.set _Z4mega6Params.has_recursion, 0
	.set _Z4mega6Params.has_indirect_call, 0

; __global__ void __launch_bounds__(NTHR, 2) mega(Params pv) {
amdhsa.kernels:
  - .agpr_count:     0
    .args:
      - .offset:         0
        .size:           184
        .value_kind:     by_value
      - .offset:         184
        .size:           4
        .value_kind:     hidden_block_count_x
      - .offset:         188
        .size:           4
        .value_kind:     hidden_block_count_y
      - .offset:         192
        .size:           4
        .value_kind:     hidden_block_count_z
      - .offset:         196
        .size:           2
        .value_kind:     hidden_group_size_x
      - .offset:         198
        .size:           2
        .value_kind:     hidden_group_size_y
      - .offset:         200
        .size:           2
        .value_kind:     hidden_group_size_z
      - .offset:         202
        .size:           2
        .value_kind:     hidden_remainder_x
      - .offset:         204
        .size:           2
        .value_kind:     hidden_remainder_y
      - .offset:         206
        .size:           2
        .value_kind:     hidden_remainder_z
      - .offset:         224
        .size:           8
        .value_kind:     hidden_global_offset_x
      - .offset:         232
        .size:           8
        .value_kind:     hidden_global_offset_y
      - .offset:         240
        .size:           8
        .value_kind:     hidden_global_offset_z
      - .offset:         248
        .size:           2
        .value_kind:     hidden_grid_dims
      - .offset:         272
        .size:           8
        .value_kind:     hidden_multigrid_sync_arg
      - .offset:         304
        .size:           4
        .value_kind:     hidden_dynamic_lds_size
    .group_segment_fixed_size: 0
    .kernarg_segment_align: 8
    .kernarg_segment_size: 440
    .language:       OpenCL C
    .language_version:
      - 2
      - 0
    .max_flat_workgroup_size: 512
    .name:           _Z4mega6Params
    .private_segment_fixed_size: 0
    .sgpr_count:     108
    .sgpr_spill_count: 4
    .symbol:         _Z4mega6Params.kd
    .uniform_work_group_size: 1
    .uses_dynamic_stack: false
    .vgpr_count:     256
    .vgpr_spill_count: 0
    .wavefront_size: 64
